# attention softmax under PV MFMAs + work-queue id prefetched one item ahead, no VMEM drain at pop
# baseline (speedup 1.0000x reference)
.LBB0_521:
	s_mov_b32 s0, s93
	v_readlane_b32 s4, v253, 54
	v_mbcnt_lo_u32_b32 v0, -1, s0
	v_mbcnt_hi_u32_b32 v0, -1, v0
	v_or_b32_e32 v0, s84, v0
	s_mov_b32 s0, s88
	v_readlane_b32 s6, v253, 56
	v_readlane_b32 s0, v254, 52
	v_readlane_b32 s8, v253, 58
	v_readlane_b32 s1, v254, 53
	s_lshl_b32 s92, s0, 6
	s_mov_b32 s8, s0
	s_lshl_b64 s[0:1], s[92:93], 2
	v_readlane_b32 s6, v253, 20
	v_readlane_b32 s62, v253, 0
	s_add_u32 s66, s6, s0
	v_readlane_b32 s0, v253, 21
	v_readlane_b32 s63, v253, 1
	s_addc_u32 s67, s0, s1
	s_add_u32 s40, s62, 0x18b00000
	s_addc_u32 s41, s63, 0
	s_add_u32 s42, s62, 0x1bb00000
	s_addc_u32 s43, s63, 0
	s_add_u32 s44, s62, 0x1ed00000
	s_addc_u32 s45, s63, 0
	s_add_u32 s48, s62, 0x3cf00000
	s_addc_u32 s49, s63, 0
	s_lshl_b32 s52, s8, 2
	s_add_u32 s53, s62, 0x2df00000
	s_addc_u32 s58, s63, 0
	s_add_u32 s59, s62, 0x30f00000
	s_addc_u32 s80, s63, 0
	s_add_u32 s81, s62, 0x200000
	s_addc_u32 s68, s63, 0
	v_readlane_b32 s5, v253, 55
	v_readlane_b32 s18, v254, 4
	v_readlane_b32 s19, v254, 5
	s_add_u32 s54, s62, 0x12b00000
	s_mov_b32 s96, 0x10000
	s_mov_b32 s91, 0x30000
	s_mov_b64 s[64:65], s[18:19]
	v_cmp_eq_u32_e64 s[4:5], 0, v0
	s_addc_u32 s55, s63, 0
	v_readlane_b32 s7, v253, 57
	v_readlane_b32 s9, v253, 59
	v_readlane_b32 s10, v253, 60
	v_readlane_b32 s11, v253, 61
	v_readlane_b32 s12, v253, 62
	v_readlane_b32 s13, v253, 63
	v_readlane_b32 s14, v254, 0
	v_readlane_b32 s15, v254, 1
	v_readlane_b32 s16, v254, 2
	v_readlane_b32 s17, v254, 3
	s_and_saveexec_b64 s[8:9], s[4:5]
	s_cbranch_execz .Lq_init_skip
	v_mov_b32_e32 v255, 1
	global_atomic_add v255, v97, v255, s[66:67] sc0
	s_waitcnt vmcnt(0)
.Lq_init_skip:
	s_or_b64 exec, exec, s[8:9]
	s_branch .LBB0_524

.LBB0_524:
	s_and_saveexec_b64 s[6:7], s[4:5]
	s_cbranch_execz .LBB0_528
	v_mov_b32_e32 v1, s31
	s_nop 0
	ds_write_b32 v1, v255
.LBB0_528:
	s_or_b64 exec, exec, s[6:7]
	v_mov_b32_e32 v0, s31
	s_waitcnt lgkmcnt(0)
	s_barrier
	ds_read_b32 v0, v0
	s_movk_i32 s1, 0x81f
	s_mov_b64 s[6:7], -1
	s_waitcnt lgkmcnt(0)
	s_barrier
	s_and_saveexec_b64 s[8:9], s[4:5]
	s_cbranch_execz .Lq_skip
	v_mov_b32_e32 v255, 1
	global_atomic_add v255, v97, v255, s[66:67] sc0
.Lq_skip:
	s_or_b64 exec, exec, s[8:9]
	v_cmp_lt_i32_e32 vcc, s1, v0
	v_readfirstlane_b32 s0, v0
	s_cbranch_vccnz .LBB0_523
	s_cmp_lt_i32 s0, 32
	s_cselect_b64 s[56:57], -1, 0
	s_add_i32 s1, s0, 0xfffffde0
	s_cmpk_lt_u32 s1, 0x200
	s_cselect_b64 s[6:7], -1, 0
	s_or_b64 s[6:7], s[56:57], s[6:7]
	s_andn2_b64 vcc, exec, s[6:7]
	s_mov_b64 s[6:7], -1
	s_cbranch_vccz .LBB0_555
	s_sub_i32 s6, s0, 32
	s_cmpk_lt_u32 s0, 0x220
	s_cselect_b32 s46, s6, s1
	s_cmpk_gt_u32 s46, 0x1ff
	s_mov_b64 s[6:7], -1
	s_cbranch_scc0 .LBB0_532
	s_lshl_b32 s6, s46, 3
	s_and_b32 s6, s6, 0x3f00
	s_lshr_b32 s1, s46, 2
	s_add_i32 s36, s6, 0xfffff000
	s_mov_b64 s[6:7], 0

	.amdhsa_kernel _Z4mega4Args
		.amdhsa_group_segment_fixed_size 0
		.amdhsa_private_segment_fixed_size 0
		.amdhsa_kernarg_size 544
		.amdhsa_user_sgpr_count 2
		.amdhsa_user_sgpr_dispatch_ptr 0
		.amdhsa_user_sgpr_queue_ptr 0
		.amdhsa_user_sgpr_kernarg_segment_ptr 1
		.amdhsa_user_sgpr_dispatch_id 0
		.amdhsa_user_sgpr_kernarg_preload_length 0
		.amdhsa_user_sgpr_kernarg_preload_offset 0
		.amdhsa_user_sgpr_private_segment_size 0
		.amdhsa_uses_dynamic_stack 0
		.amdhsa_enable_private_segment 0
		.amdhsa_system_sgpr_workgroup_id_x 1
		.amdhsa_system_sgpr_workgroup_id_y 0
		.amdhsa_system_sgpr_workgroup_id_z 0
		.amdhsa_system_sgpr_workgroup_info 0
		.amdhsa_system_vgpr_workitem_id 0
		.amdhsa_next_free_vgpr 256
		.amdhsa_next_free_sgpr 100
		.amdhsa_accum_offset 256
		.amdhsa_reserve_vcc 1
		.amdhsa_float_round_mode_32 0
		.amdhsa_float_round_mode_16_64 0
		.amdhsa_float_denorm_mode_32 3
		.amdhsa_float_denorm_mode_16_64 3
		.amdhsa_dx10_clamp 1
		.amdhsa_ieee_mode 1
		.amdhsa_fp16_overflow 0
		.amdhsa_tg_split 0
		.amdhsa_exception_fp_ieee_invalid_op 0
		.amdhsa_exception_fp_denorm_src 0
		.amdhsa_exception_fp_ieee_div_zero 0
		.amdhsa_exception_fp_ieee_overflow 0
		.amdhsa_exception_fp_ieee_underflow 0
		.amdhsa_exception_fp_ieee_inexact 0
		.amdhsa_exception_int_div_zero 0
	.end_amdhsa_kernel

.Lfunc_end0:
	.size	_Z4mega4Args, .Lfunc_end0-_Z4mega4Args
	.set _Z4mega4Args.num_vgpr, 256
	.set _Z4mega4Args.num_agpr, 0
	.set _Z4mega4Args.numbered_sgpr, 100
	.set _Z4mega4Args.num_named_barrier, 0
	.set _Z4mega4Args.private_seg_size, 0
	.set _Z4mega4Args.uses_vcc, 1
	.set _Z4mega4Args.uses_flat_scratch, 0
	.set _Z4mega4Args.has_dyn_sized_stack, 0
	.set _Z4mega4Args.has_recursion, 0
	.set _Z4mega4Args.has_indirect_call, 0

amdhsa.kernels:
  - .agpr_count:     0
    .args:
      - .offset:         0
        .size:           288
        .value_kind:     by_value
      - .offset:         288
        .size:           4
        .value_kind:     hidden_block_count_x
      - .offset:         292
        .size:           4
        .value_kind:     hidden_block_count_y
      - .offset:         296
        .size:           4
        .value_kind:     hidden_block_count_z
      - .offset:         300
        .size:           2
        .value_kind:     hidden_group_size_x
      - .offset:         302
        .size:           2
        .value_kind:     hidden_group_size_y
      - .offset:         304
        .size:           2
        .value_kind:     hidden_group_size_z
      - .offset:         306
        .size:           2
        .value_kind:     hidden_remainder_x
      - .offset:         308
        .size:           2
        .value_kind:     hidden_remainder_y
      - .offset:         310
        .size:           2
        .value_kind:     hidden_remainder_z
      - .offset:         328
        .size:           8
        .value_kind:     hidden_global_offset_x
      - .offset:         336
        .size:           8
        .value_kind:     hidden_global_offset_y
      - .offset:         344
        .size:           8
        .value_kind:     hidden_global_offset_z
      - .offset:         352
        .size:           2
        .value_kind:     hidden_grid_dims
      - .offset:         408
        .size:           4
        .value_kind:     hidden_dynamic_lds_size
    .group_segment_fixed_size: 0
    .kernarg_segment_align: 8
    .kernarg_segment_size: 544
    .language:       OpenCL C
    .language_version:
      - 2
      - 0
    .max_flat_workgroup_size: 512
    .name:           _Z4mega4Args
    .private_segment_fixed_size: 0
    .sgpr_count:     106
    .sgpr_spill_count: 146
    .symbol:         _Z4mega4Args.kd
    .uniform_work_group_size: 1
    .uses_dynamic_stack: false
    .vgpr_count:     256
    .vgpr_spill_count: 0
    .wavefront_size: 64
